# SWA QK fragment reads double-buffered, bias reads ahead of shortened MFMA padding (SWA+FoX), residual epilogues load both column halves of a row group together
# baseline (speedup 1.0000x reference)
; #define LAS __attribute__((address_space(3)))
; DI int crow(int r, int hi) { return (r & 3) + 8 * (r >> 2) + 4 * hi; }
; #define MFMA32(a, b, c) __builtin_amdgcn_mfma_f32_32x32x16_bf16((a), (b), (c), 0, 0, 0)
; template <int MODE> DI void attn_unit(int b, int qb, const bf16* Qb, int qpitch, const bf16* Kb, int kpitch, const bf16* VT, bf16* O, float* ssq, ...
;     ...
;         if (active) {
;             const LAS unsigned char* kb = lds + KOFF + buf * KSZ + r32 * PK + 16 * hi;
;             v16f p0, p1;
; #pragma unroll
;             for (int d0 = 0; d0 < ND; ++d0) {
;                 const v8s ka = *(const LAS v8s*)(kb + 32 * d0), kb2 = *(const LAS v8s*)(kb + 32 * PK + 32 * d0);
;                 if (d0 == 0) { p0 = MFMA32(ka, qr[0], (v16f){}); p1 = MFMA32(kb2, qr[0], (v16f){}); }
;                 else { p0 = MFMA32(ka, qr[d0], p0); p1 = MFMA32(kb2, qr[d0], p1); }
;             }
;             asm volatile("s_nop 15\n\ts_nop 7" : "+v"(p0), "+v"(p1));
;             if (MODE == 1) {
;                 const LAS float* fb = (const LAS float*)(lds + FOFF + buf * 256);
; #pragma unroll
;                 for (int g = 0; g < 4; ++g) {
;                     const v4f f0 = *(const LAS v4f*)(fb + 8 * g + 4 * hi), f1 = *(const LAS v4f*)(fb + 32 + 8 * g + 4 * hi);
; #pragma unroll
;                     for (int i = 0; i < 4; ++i) { p0[4 * g + i] += f0[i]; p1[4 * g + i] += f1[i]; }
;                 }
;             }
;             if (MODE == 0) {
;                 const LAS float* tb = MS + (223 - q + k0 + 4 * hi);
; #pragma unroll
;                 for (int r = 0; r < 16; ++r) { p0[r] += tb[(r & 3) + 8 * (r >> 2)]; p1[r] += tb[32 + (r & 3) + 8 * (r >> 2)]; }
;             } else if (k0 + 63 > qw0) {
; #pragma unroll
;                 for (int r = 0; r < 16; ++r) {
;                     const int kv = k0 + crow(r, hi);
;                     if (kv > q) p0[r] = NEGBIG;
;                     if (kv + 32 > q) p1[r] = NEGBIG;
;                 }
.LBB0_509:
	s_mul_i32 s24, s72, 0x2400
	v_add_u32_e32 v172, s24, v199
	ds_read_b128 v[32:35], v172 offset:4608
	ds_read_b128 v[36:39], v172
	ds_read_b128 v[182:185], v172 offset:32
	ds_read_b128 v[186:189], v172 offset:4640
	s_add_i32 s24, s59, 0xff
	s_cmp_le_i32 s24, s15
	s_waitcnt lgkmcnt(2)
	v_mfma_f32_32x32x16_bf16 v[48:63], v[36:39], v[66:69], 0
	v_mfma_f32_32x32x16_bf16 v[32:47], v[32:35], v[66:69], 0
	s_waitcnt lgkmcnt(1)
	v_mfma_f32_32x32x16_bf16 v[48:63], v[182:185], v[70:73], v[48:63]
	s_waitcnt lgkmcnt(0)
	v_mfma_f32_32x32x16_bf16 v[32:47], v[186:189], v[70:73], v[32:47]
	ds_read_b128 v[182:185], v172 offset:4672
	ds_read_b128 v[186:189], v172 offset:64
	s_waitcnt lgkmcnt(0)
	v_mfma_f32_32x32x16_bf16 v[48:63], v[186:189], v[74:77], v[48:63]
	v_mfma_f32_32x32x16_bf16 v[32:47], v[182:185], v[74:77], v[32:47]
	ds_read_b128 v[182:185], v172 offset:4704
	ds_read_b128 v[186:189], v172 offset:96
	v_lshl_add_u32 v172, s72, 8, v202
	s_waitcnt lgkmcnt(0)
	v_mfma_f32_32x32x16_bf16 v[48:63], v[186:189], v[78:81], v[48:63]
	v_mfma_f32_32x32x16_bf16 v[32:47], v[182:185], v[78:81], v[32:47]
	ds_read_b128 v[182:185], v172 offset:35840
	ds_read_b128 v[218:221], v172 offset:35872
	ds_read_b128 v[222:225], v172 offset:35968
	ds_read_b128 v[242:245], v172 offset:36000
	s_nop 7
	s_waitcnt lgkmcnt(3)
	v_pk_add_f32 v[188:189], v[182:183], v[48:49]
	v_pk_add_f32 v[186:187], v[184:185], v[50:51]
	s_waitcnt lgkmcnt(2)
	v_pk_add_f32 v[184:185], v[52:53], v[218:219]
	v_pk_add_f32 v[182:183], v[54:55], v[220:221]
	ds_read_b128 v[48:51], v172 offset:35904
	ds_read_b128 v[218:221], v172 offset:36032
	s_waitcnt lgkmcnt(2)
	v_pk_add_f32 v[38:39], v[38:39], v[244:245]
	v_pk_add_f32 v[34:35], v[34:35], v[224:225]
	v_pk_add_f32 v[32:33], v[32:33], v[222:223]
	s_waitcnt lgkmcnt(1)
	v_pk_add_f32 v[54:55], v[56:57], v[48:49]
	v_pk_add_f32 v[48:49], v[58:59], v[50:51]
	ds_read_b128 v[56:59], v172 offset:35936
	ds_read_b128 v[246:249], v172 offset:36064
	s_waitcnt lgkmcnt(1)
	v_pk_add_f32 v[52:53], v[60:61], v[56:57]
	v_pk_add_f32 v[50:51], v[62:63], v[58:59]
	s_waitcnt lgkmcnt(0)
	v_pk_add_f32 v[44:45], v[44:45], v[246:247]
	v_pk_add_f32 v[56:57], v[40:41], v[218:219]
	v_pk_add_f32 v[58:59], v[36:37], v[242:243]
	v_pk_add_f32 v[36:37], v[46:47], v[248:249]
	v_pk_add_f32 v[40:41], v[42:43], v[220:221]
	s_cbranch_scc1 .LBB0_511
	v_add_u32_e32 v42, s59, v194
	v_add_u32_e32 v46, 0xe0, v42
	v_add_u32_e32 v43, 0xc0, v42
	v_cmp_le_i32_e32 vcc, v46, v168
	s_nop 1
	v_cndmask_b32_e32 v32, v234, v32, vcc
	v_cmp_le_i32_e32 vcc, v43, v168
	s_nop 1
	v_cndmask_b32_e32 v188, v234, v188, vcc
	v_cmp_lt_i32_e32 vcc, v43, v168
	v_add_u32_e32 v43, 0xe1, v42
	s_nop 0
	v_cndmask_b32_e32 v189, v234, v189, vcc
	v_cmp_le_i32_e32 vcc, v43, v168
	v_add_u32_e32 v43, 0xc2, v42
	s_nop 0
	v_cndmask_b32_e32 v33, v234, v33, vcc
	v_cmp_le_i32_e32 vcc, v43, v168
	v_add_u32_e32 v43, 0xe2, v42
	s_nop 0
	v_cndmask_b32_e32 v186, v234, v186, vcc
	v_cmp_le_i32_e32 vcc, v43, v168
	v_add_u32_e32 v43, 0xc3, v42
	s_nop 0
	v_cndmask_b32_e32 v34, v234, v34, vcc
	v_cmp_le_i32_e32 vcc, v43, v168
	v_add_u32_e32 v43, 0xe3, v42
	s_nop 0
	v_cndmask_b32_e32 v187, v234, v187, vcc
	v_cmp_le_i32_e32 vcc, v43, v168
	v_add_u32_e32 v43, 0xc8, v42
	s_nop 0
	v_cndmask_b32_e32 v35, v234, v35, vcc
	v_cmp_le_i32_e32 vcc, v43, v168
	v_add_u32_e32 v43, 0xe8, v42
	s_nop 0
	v_cndmask_b32_e32 v184, v234, v184, vcc
	v_cmp_le_i32_e32 vcc, v43, v168
	v_add_u32_e32 v43, 0xc9, v42
	s_nop 0
	v_cndmask_b32_e32 v58, v234, v58, vcc
	v_cmp_le_i32_e32 vcc, v43, v168
	v_add_u32_e32 v43, 0xe9, v42
	s_nop 0
	v_cndmask_b32_e32 v185, v234, v185, vcc
	v_cmp_le_i32_e32 vcc, v43, v168
	v_add_u32_e32 v43, 0xca, v42
	s_nop 0
	v_cndmask_b32_e32 v59, v234, v59, vcc
	v_cmp_le_i32_e32 vcc, v43, v168
	v_add_u32_e32 v43, 0xea, v42
	s_nop 0
	v_cndmask_b32_e32 v182, v234, v182, vcc
	v_cmp_le_i32_e32 vcc, v43, v168
	v_add_u32_e32 v43, 0xcb, v42
	s_nop 0
	v_cndmask_b32_e32 v38, v234, v38, vcc
	v_cmp_le_i32_e32 vcc, v43, v168
	v_add_u32_e32 v43, 0xeb, v42
	s_nop 0
	v_cndmask_b32_e32 v183, v234, v183, vcc
	v_cmp_le_i32_e32 vcc, v43, v168
	v_add_u32_e32 v43, 0xd0, v42
	s_nop 0
	v_cndmask_b32_e32 v39, v234, v39, vcc
	v_cmp_le_i32_e32 vcc, v43, v168
	v_add_u32_e32 v43, 0xf0, v42
	s_nop 0
	v_cndmask_b32_e32 v54, v234, v54, vcc
	v_cmp_le_i32_e32 vcc, v43, v168
	v_add_u32_e32 v43, 0xd1, v42
	s_nop 0
	v_cndmask_b32_e32 v56, v234, v56, vcc
	v_cmp_le_i32_e32 vcc, v43, v168
	v_add_u32_e32 v43, 0xf1, v42
	s_nop 0
	v_cndmask_b32_e32 v55, v234, v55, vcc
	v_cmp_le_i32_e32 vcc, v43, v168
	v_add_u32_e32 v43, 0xd2, v42
	s_nop 0
	v_cndmask_b32_e32 v57, v234, v57, vcc
	v_cmp_le_i32_e32 vcc, v43, v168
	v_add_u32_e32 v43, 0xf2, v42
	s_nop 0
	v_cndmask_b32_e32 v48, v234, v48, vcc
	v_cmp_le_i32_e32 vcc, v43, v168
	v_add_u32_e32 v43, 0xd3, v42
	s_nop 0
	v_cndmask_b32_e32 v40, v234, v40, vcc
	v_cmp_le_i32_e32 vcc, v43, v168
	v_add_u32_e32 v43, 0xf3, v42
	s_nop 0
	v_cndmask_b32_e32 v49, v234, v49, vcc
	v_cmp_le_i32_e32 vcc, v43, v168
	v_add_u32_e32 v43, 0xd8, v42
	s_nop 0
	v_cndmask_b32_e32 v41, v234, v41, vcc
	v_cmp_le_i32_e32 vcc, v43, v168
	v_add_u32_e32 v43, 0xf8, v42
	s_nop 0
	v_cndmask_b32_e32 v52, v234, v52, vcc
	v_cmp_le_i32_e32 vcc, v43, v168
	v_add_u32_e32 v43, 0xd9, v42
	s_nop 0
	v_cndmask_b32_e32 v44, v234, v44, vcc
	v_cmp_le_i32_e32 vcc, v43, v168
	v_add_u32_e32 v43, 0xf9, v42
	s_nop 0
	v_cndmask_b32_e32 v53, v234, v53, vcc
	v_cmp_le_i32_e32 vcc, v43, v168
	v_add_u32_e32 v43, 0xda, v42
	s_nop 0
	v_cndmask_b32_e32 v45, v234, v45, vcc
	v_cmp_le_i32_e32 vcc, v43, v168
	v_add_u32_e32 v43, 0xfa, v42
	s_nop 0
	v_cndmask_b32_e32 v50, v234, v50, vcc
	v_cmp_le_i32_e32 vcc, v43, v168
	v_add_u32_e32 v43, 0xdb, v42
	v_add_u32_e32 v42, 0xfb, v42
	v_cndmask_b32_e32 v36, v234, v36, vcc
	v_cmp_le_i32_e32 vcc, v43, v168
	s_nop 1
	v_cndmask_b32_e32 v51, v234, v51, vcc
	v_cmp_le_i32_e32 vcc, v42, v168
	s_nop 1
	v_cndmask_b32_e32 v37, v234, v37, vcc

; #define LAS __attribute__((address_space(3)))
; template <int MODE> DI void attn_unit(int b, int qb, const bf16* Qb, int qpitch, const bf16* Kb, int kpitch, const bf16* VT, bf16* O, float* ssq, ...
;     ...
;         if (active) {
;             const LAS unsigned char* kb = lds + KOFF + buf * KSZ + r32 * PK + 16 * hi;
;             v16f p0, p1;
; #pragma unroll
;             for (int d0 = 0; d0 < ND; ++d0) {
;                 const v8s ka = *(const LAS v8s*)(kb + 32 * d0), kb2 = *(const LAS v8s*)(kb + 32 * PK + 32 * d0);
;                 if (d0 == 0) { p0 = MFMA32(ka, qr[0], (v16f){}); p1 = MFMA32(kb2, qr[0], (v16f){}); }
;                 else { p0 = MFMA32(ka, qr[d0], p0); p1 = MFMA32(kb2, qr[d0], p1); }
;             }
;             asm volatile("s_nop 15\n\ts_nop 7" : "+v"(p0), "+v"(p1));
;             if (MODE == 1) {
;                 const LAS float* fb = (const LAS float*)(lds + FOFF + buf * 256);
; #pragma unroll
;                 for (int g = 0; g < 4; ++g) {
;                     const v4f f0 = *(const LAS v4f*)(fb + 8 * g + 4 * hi), f1 = *(const LAS v4f*)(fb + 32 + 8 * g + 4 * hi);
; #pragma unroll
;                     for (int i = 0; i < 4; ++i) { p0[4 * g + i] += f0[i]; p1[4 * g + i] += f1[i]; }
;                 }
;             }
;             if (MODE == 0) {
;                 const LAS float* tb = MS + (223 - q + k0 + 4 * hi);
; #pragma unroll
;                 for (int r = 0; r < 16; ++r) { p0[r] += tb[(r & 3) + 8 * (r >> 2)]; p1[r] += tb[32 + (r & 3) + 8 * (r >> 2)]; }
;             } else if (k0 + 63 > qw0) {
; #pragma unroll
;                 for (int r = 0; r < 16; ++r) {
;                     const int kv = k0 + crow(r, hi);
;                     if (kv > q) p0[r] = NEGBIG;
;                     if (kv + 32 > q) p1[r] = NEGBIG;
;                 }
;             }
;             float rm;
;             { float ma = max3f(p0[0], p0[1], p1[0]), mb = max3f(p0[2], p0[3], p1[1]); ma = max3f(ma, p1[2], p1[3]);
; #pragma unroll
;               for (int r = 4; r < 16; r += 4) { ma = max3f(ma, p0[r], p0[r + 1]); mb = max3f(mb, p0[r + 2], p0[r + 3]); ma = max3f(ma, p1[r], p1[r + 1]); mb = max3f(mb, p1[r + 2], p1[r + 3]); }
;               rm = max2f(ma, mb); }
;             { const auto rr = __builtin_amdgcn_permlane32_swap(__float_as_uint(rm), __float_as_uint(rm), false, false); rm = max2f(__uint_as_float(rr[0]), __uint_as_float(rr[1])); }
.LBB0_534:
	s_cmp_le_i32 s18, s27
	s_cselect_b64 s[74:75], -1, 0
	s_add_i32 s19, s18, 63
	s_cmp_ge_i32 s19, s36
	s_cselect_b64 s[84:85], -1, 0
	s_and_b64 s[74:75], s[74:75], s[84:85]
	s_andn2_b64 vcc, exec, s[74:75]
	s_cbranch_vccnz .LBB0_538
	s_mul_i32 s19, s59, 0x2400
	v_add_u32_e32 v163, s19, v199
	ds_read_b128 v[32:35], v163
	ds_read_b128 v[164:167], v163 offset:32
	ds_read_b128 v[48:51], v163 offset:4608
	ds_read_b128 v[236:239], v163 offset:4640
	s_waitcnt lgkmcnt(3)
	v_mfma_f32_32x32x16_bf16 v[32:47], v[32:35], v[66:69], 0
	s_waitcnt lgkmcnt(2)
	v_mfma_f32_32x32x16_bf16 v[32:47], v[164:167], v[70:73], v[32:47]
	ds_read_b128 v[164:167], v163 offset:64
	s_waitcnt lgkmcnt(2)
	v_mfma_f32_32x32x16_bf16 v[48:63], v[48:51], v[66:69], 0
	s_waitcnt lgkmcnt(1)
	v_mfma_f32_32x32x16_bf16 v[48:63], v[236:239], v[70:73], v[48:63]
	ds_read_b128 v[236:239], v163 offset:4672
	s_waitcnt lgkmcnt(1)
	v_mfma_f32_32x32x16_bf16 v[32:47], v[164:167], v[74:77], v[32:47]
	ds_read_b128 v[164:167], v163 offset:96
	s_waitcnt lgkmcnt(1)
	v_mfma_f32_32x32x16_bf16 v[48:63], v[236:239], v[74:77], v[48:63]
	ds_read_b128 v[236:239], v163 offset:4704
	s_waitcnt lgkmcnt(1)
	v_mfma_f32_32x32x16_bf16 v[32:47], v[164:167], v[78:81], v[32:47]
	s_waitcnt lgkmcnt(0)
	v_mfma_f32_32x32x16_bf16 v[48:63], v[236:239], v[78:81], v[48:63]
	ds_read2_b32 v[166:167], v153 offset1:1
	ds_read2_b32 v[168:169], v153 offset0:32 offset1:33
	ds_read2_b32 v[176:177], v153 offset0:2 offset1:3
	ds_read2_b32 v[178:179], v153 offset0:34 offset1:35
	ds_read2_b32 v[180:181], v153 offset0:40 offset1:41
	s_nop 7
	s_waitcnt lgkmcnt(4)
	s_nop 2
	v_add_f32_e32 v163, v166, v32
	v_add_f32_e32 v164, v33, v167
	ds_read2_b32 v[32:33], v153 offset0:8 offset1:9
	s_waitcnt lgkmcnt(4)
	v_add_f32_e32 v165, v48, v168
	v_add_f32_e32 v49, v49, v169
	s_waitcnt lgkmcnt(3)
	v_add_f32_e32 v48, v34, v176
	s_waitcnt lgkmcnt(2)
	v_add_f32_e32 v167, v50, v178
	v_add_f32_e32 v166, v35, v177
	s_waitcnt lgkmcnt(0)
	v_add_f32_e32 v50, v36, v32
	ds_read2_b32 v[34:35], v153 offset0:10 offset1:11
	ds_read2_b32 v[176:177], v153 offset0:42 offset1:43
	v_add_f32_e32 v169, v37, v33
	ds_read2_b32 v[32:33], v153 offset0:16 offset1:17
	v_add_f32_e32 v51, v51, v179
	v_add_f32_e32 v168, v53, v181
	s_waitcnt lgkmcnt(2)
	v_add_f32_e32 v53, v38, v34
	s_waitcnt lgkmcnt(1)
	v_add_f32_e32 v179, v54, v176
	ds_read2_b32 v[36:37], v153 offset0:48 offset1:49
	v_add_f32_e32 v178, v39, v35
	v_add_f32_e32 v176, v55, v177
	s_waitcnt lgkmcnt(1)
	v_add_f32_e32 v55, v40, v32
	ds_read2_b32 v[34:35], v153 offset0:18 offset1:19
	ds_read2_b32 v[38:39], v153 offset0:50 offset1:51
	v_add_f32_e32 v177, v41, v33
	ds_read2_b32 v[32:33], v153 offset0:24 offset1:25
	v_add_f32_e32 v52, v52, v180
	s_waitcnt lgkmcnt(3)
	v_add_f32_e32 v180, v56, v36
	v_add_f32_e32 v56, v57, v37
	s_waitcnt lgkmcnt(2)
	v_add_f32_e32 v54, v42, v34
	s_waitcnt lgkmcnt(0)
	v_add_f32_e32 v36, v44, v32
	v_max3_f32 v32, v163, v164, v165
	v_add_f32_e32 v40, v45, v33
	v_max3_f32 v33, v48, v166, v49
	v_max3_f32 v32, v32, v167, v51
	v_add_f32_e32 v57, v58, v38
	v_add_f32_e32 v43, v43, v35
	ds_read2_b32 v[34:35], v153 offset0:56 offset1:57
	v_add_f32_e32 v39, v59, v39
	ds_read2_b32 v[58:59], v153 offset0:26 offset1:27
	ds_read2_b32 v[182:183], v153 offset0:58 offset1:59
	v_max3_f32 v32, v32, v50, v169
	v_max3_f32 v33, v33, v53, v178
	s_waitcnt lgkmcnt(2)
	v_add_f32_e32 v38, v60, v34
	v_max3_f32 v32, v32, v52, v168
	v_max3_f32 v33, v33, v179, v176
	s_waitcnt lgkmcnt(1)
	v_add_f32_e32 v41, v46, v58
	v_max3_f32 v32, v32, v55, v177
	v_max3_f32 v33, v33, v54, v43
	v_add_f32_e32 v42, v47, v59
	v_max3_f32 v32, v32, v180, v56
	v_max3_f32 v33, v33, v57, v39
	v_add_f32_e32 v34, v61, v35
	v_max3_f32 v32, v32, v36, v40
	v_max3_f32 v33, v33, v41, v42
	s_waitcnt lgkmcnt(0)
	v_add_f32_e32 v37, v62, v182
	v_add_f32_e32 v35, v63, v183
	v_max3_f32 v32, v32, v38, v34
	v_max3_f32 v33, v33, v37, v35
	v_max_f32_e32 v32, v32, v33
	v_mov_b32_e32 v33, v32
	s_nop 1
	v_permlane32_swap_b32_e32 v32, v33
	v_max_f32_e32 v32, v32, v33
	v_max_f32_e32 v33, v157, v32
	v_sub_f32_e32 v32, v157, v33
	v_exp_f32_e32 v32, v32
	s_nop 0
	v_cmp_neq_f32_e32 vcc, 1.0, v32
	s_cbranch_vccz .LBB0_537
	v_pk_mul_f32 v[14:15], v[14:15], v[32:33] op_sel_hi:[1,0]
	v_pk_mul_f32 v[12:13], v[12:13], v[32:33] op_sel_hi:[1,0]
	v_pk_mul_f32 v[10:11], v[10:11], v[32:33] op_sel_hi:[1,0]
	v_pk_mul_f32 v[8:9], v[8:9], v[32:33] op_sel_hi:[1,0]
	v_pk_mul_f32 v[6:7], v[6:7], v[32:33] op_sel_hi:[1,0]
	v_pk_mul_f32 v[4:5], v[4:5], v[32:33] op_sel_hi:[1,0]
	v_pk_mul_f32 v[2:3], v[2:3], v[32:33] op_sel_hi:[1,0]
	v_pk_mul_f32 v[0:1], v[0:1], v[32:33] op_sel_hi:[1,0]
	v_pk_mul_f32 v[30:31], v[30:31], v[32:33] op_sel_hi:[1,0]
	v_pk_mul_f32 v[28:29], v[28:29], v[32:33] op_sel_hi:[1,0]
	v_pk_mul_f32 v[26:27], v[26:27], v[32:33] op_sel_hi:[1,0]
	v_pk_mul_f32 v[24:25], v[24:25], v[32:33] op_sel_hi:[1,0]
	v_pk_mul_f32 v[22:23], v[22:23], v[32:33] op_sel_hi:[1,0]
	v_pk_mul_f32 v[20:21], v[20:21], v[32:33] op_sel_hi:[1,0]
	v_pk_mul_f32 v[18:19], v[18:19], v[32:33] op_sel_hi:[1,0]
	v_pk_mul_f32 v[16:17], v[16:17], v[32:33] op_sel_hi:[1,0]
